# conv_item: 8 channels per lane (dwordx4 taps/outputs, one 16-lane DPP row per head for the l2-norm) and silu via v_rcp_f32 * x instead of the IEEE division expansion; on top of v74
# speedup vs baseline: 1.0448x; 1.0050x over previous
.LBB0_256:
	v_mov_b32_e32 v20, v217
	v_lshlrev_b32_e32 v21, 4, v0
	v_ashrrev_i32_e32 v22, 4, v20
	v_and_b32_e32 v0, -4, v22
	v_lshlrev_b32_e32 v1, 5, v1
	v_add3_u32 v10, v228, v1, v0
	v_add_u32_e32 v23, v0, v21
	v_mad_i64_i32 v[0:1], s[0:1], v10, s33, 0
	v_and_b32_e32 v2, 63, v20
	v_lshlrev_b32_e32 v12, 2, v2
	v_readlane_b32 s0, v252, 19
	v_ashrrev_i32_e32 v11, 31, v10
	v_or_b32_e32 v0, v0, v12
	v_readlane_b32 s1, v252, 20
	v_lshlrev_b64 v[6:7], 11, v[10:11]
	v_lshlrev_b32_e32 v16, 3, v2
	v_lshl_add_u64 v[0:1], s[0:1], 0, v[0:1]
	v_mad_i64_i32 v[10:11], s[0:1], v10, s21, 0
	v_or_b32_e32 v6, v6, v12
	v_or_b32_e32 v10, v10, v12
	v_lshl_add_u64 v[2:3], s[60:61], 0, v[16:17]
	v_lshl_add_u64 v[4:5], s[62:63], 0, v[16:17]
	v_lshl_add_u64 v[6:7], s[6:7], 0, v[6:7]
	v_lshl_add_u64 v[8:9], s[64:65], 0, v[16:17]
	v_lshl_add_u64 v[10:11], s[6:7], 0, v[10:11]
	s_mov_b32 s70, 0
	v_lshl_add_u32 v14, v12, 1, v12
	v_mov_b32_e32 v15, 0
	v_lshl_add_u64 v[0:1], v[0:1], 0, v[14:15]
	v_lshl_add_u64 v[6:7], v[6:7], 0, v[14:15]
	v_lshl_add_u64 v[10:11], v[10:11], 0, v[14:15]
	v_lshl_add_u32 v14, v16, 1, v16
	v_lshl_add_u64 v[2:3], v[2:3], 0, v[14:15]
	v_lshl_add_u64 v[4:5], v[4:5], 0, v[14:15]
	v_lshl_add_u64 v[8:9], v[8:9], 0, v[14:15]
	s_and_b64 vcc, exec, s[10:11]
	s_cbranch_vccz .Lcv_even
	s_mov_b64 s[68:69], 0x1000
	v_lshl_add_u64 v[162:163], v[2:3], 0, s[68:69]
	global_load_dwordx4 v[36:39], v[2:3], off offset:-4096
	global_load_dwordx4 v[40:43], v[2:3], off offset:-4080
	global_load_dwordx4 v[44:47], v[2:3], off
	global_load_dwordx4 v[48:51], v[2:3], off offset:16
	global_load_dwordx4 v[52:55], v[162:163], off
	global_load_dwordx4 v[56:59], v[162:163], off offset:16
	global_load_dwordx4 v[60:63], v[4:5], off
	global_load_dwordx4 v[64:67], v[4:5], off offset:16
	global_load_dwordx4 v[68:71], v[2:3], off offset:-2048
	global_load_dwordx4 v[72:75], v[2:3], off offset:-2032
	global_load_dwordx4 v[76:79], v[2:3], off offset:2048
	global_load_dwordx4 v[80:83], v[2:3], off offset:2064
	global_load_dwordx4 v[86:89], v[162:163], off offset:2048
	global_load_dwordx4 v[90:93], v[162:163], off offset:2064
	global_load_dwordx4 v[94:97], v[4:5], off offset:2048
	global_load_dwordx4 v[98:101], v[4:5], off offset:2064
	s_waitcnt vmcnt(0)
.Lcv_odd_tok:
	v_add_u32_e32 v12, s70, v23
	v_cmp_lt_i32_e32 vcc, s2, v12
	v_mov_b32_e32 v13, 0xff
	v_mov_b32_e32 v14, 0xfff
	v_cndmask_b32_e32 v13, v13, v14, vcc
	v_and_b32_e32 v12, v13, v12
	v_cmp_ne_u32_e64 s[42:43], 0, v12
	v_cmp_ne_u32_e64 s[44:45], v12, v13
	s_mov_b64 s[68:69], 0xa91fc00
	v_lshl_add_u64 v[162:163], v[0:1], 0, s[68:69]
	s_mov_b64 s[68:69], 0xa921000
	v_lshl_add_u64 v[164:165], v[0:1], 0, s[68:69]
	s_mov_b64 s[68:69], 0xa922c00
	v_lshl_add_u64 v[166:167], v[0:1], 0, s[68:69]
	global_load_dwordx4 v[110:113], v[162:163], off
	global_load_dwordx4 v[114:117], v[164:165], off offset:1024
	global_load_dwordx4 v[118:121], v[166:167], off
	global_load_dwordx4 v[122:125], v[162:163], off offset:1024
	global_load_dwordx4 v[126:129], v[164:165], off offset:2048
	global_load_dwordx4 v[130:133], v[166:167], off offset:1024
	s_waitcnt vmcnt(3)
	v_cndmask_b32_e64 v110, 0, v110, s[42:43]
	v_cndmask_b32_e64 v118, 0, v118, s[44:45]
	v_lshlrev_b32_e32 v174, 16, v114
	v_and_b32_e32 v175, 0xffff0000, v114
	v_lshlrev_b32_e32 v176, 16, v110
	v_and_b32_e32 v177, 0xffff0000, v110
	v_lshlrev_b32_e32 v178, 16, v118
	v_and_b32_e32 v179, 0xffff0000, v118
	v_pk_mul_f32 v[150:151], v[44:45], v[174:175]
	s_nop 0
	v_pk_fma_f32 v[150:151], v[36:37], v[176:177], v[150:151]
	v_pk_fma_f32 v[150:151], v[52:53], v[178:179], v[150:151]
	v_pk_add_f32 v[150:151], v[150:151], v[60:61]
	s_nop 0
	v_mul_f32_e32 v180, 0xbfb8aa3b, v150
	v_exp_f32_e32 v186, v180
	v_mul_f32_e32 v180, 0xbfb8aa3b, v151
	v_exp_f32_e32 v187, v180
	s_nop 0
	v_pk_add_f32 v[186:187], v[186:187], 1.0 op_sel_hi:[1,0]
	s_nop 0
	v_rcp_f32_e32 v186, v186
	v_rcp_f32_e32 v187, v187
	s_nop 0
	v_pk_mul_f32 v[150:151], v[150:151], v[186:187]
	s_nop 0
	v_cndmask_b32_e64 v111, 0, v111, s[42:43]
	v_cndmask_b32_e64 v119, 0, v119, s[44:45]
	v_lshlrev_b32_e32 v174, 16, v115
	v_and_b32_e32 v175, 0xffff0000, v115
	v_lshlrev_b32_e32 v176, 16, v111
	v_and_b32_e32 v177, 0xffff0000, v111
	v_lshlrev_b32_e32 v178, 16, v119
	v_and_b32_e32 v179, 0xffff0000, v119
	v_pk_mul_f32 v[152:153], v[46:47], v[174:175]
	s_nop 0
	v_pk_fma_f32 v[152:153], v[38:39], v[176:177], v[152:153]
	v_pk_fma_f32 v[152:153], v[54:55], v[178:179], v[152:153]
	v_pk_add_f32 v[152:153], v[152:153], v[62:63]
	s_nop 0
	v_mul_f32_e32 v180, 0xbfb8aa3b, v152
	v_exp_f32_e32 v186, v180
	v_mul_f32_e32 v180, 0xbfb8aa3b, v153
	v_exp_f32_e32 v187, v180
	s_nop 0
	v_pk_add_f32 v[186:187], v[186:187], 1.0 op_sel_hi:[1,0]
	s_nop 0
	v_rcp_f32_e32 v186, v186
	v_rcp_f32_e32 v187, v187
	s_nop 0
	v_pk_mul_f32 v[152:153], v[152:153], v[186:187]
	s_nop 0
	v_cndmask_b32_e64 v112, 0, v112, s[42:43]
	v_cndmask_b32_e64 v120, 0, v120, s[44:45]
	v_lshlrev_b32_e32 v174, 16, v116
	v_and_b32_e32 v175, 0xffff0000, v116
	v_lshlrev_b32_e32 v176, 16, v112
	v_and_b32_e32 v177, 0xffff0000, v112
	v_lshlrev_b32_e32 v178, 16, v120
	v_and_b32_e32 v179, 0xffff0000, v120
	v_pk_mul_f32 v[154:155], v[48:49], v[174:175]
	s_nop 0
	v_pk_fma_f32 v[154:155], v[40:41], v[176:177], v[154:155]
	v_pk_fma_f32 v[154:155], v[56:57], v[178:179], v[154:155]
	v_pk_add_f32 v[154:155], v[154:155], v[64:65]
	s_nop 0
	v_mul_f32_e32 v180, 0xbfb8aa3b, v154
	v_exp_f32_e32 v186, v180
	v_mul_f32_e32 v180, 0xbfb8aa3b, v155
	v_exp_f32_e32 v187, v180
	s_nop 0
	v_pk_add_f32 v[186:187], v[186:187], 1.0 op_sel_hi:[1,0]
	s_nop 0
	v_rcp_f32_e32 v186, v186
	v_rcp_f32_e32 v187, v187
	s_nop 0
	v_pk_mul_f32 v[154:155], v[154:155], v[186:187]
	s_nop 0
	v_cndmask_b32_e64 v113, 0, v113, s[42:43]
	v_cndmask_b32_e64 v121, 0, v121, s[44:45]
	v_lshlrev_b32_e32 v174, 16, v117
	v_and_b32_e32 v175, 0xffff0000, v117
	v_lshlrev_b32_e32 v176, 16, v113
	v_and_b32_e32 v177, 0xffff0000, v113
	v_lshlrev_b32_e32 v178, 16, v121
	v_and_b32_e32 v179, 0xffff0000, v121
	v_pk_mul_f32 v[156:157], v[50:51], v[174:175]
	s_nop 0
	v_pk_fma_f32 v[156:157], v[42:43], v[176:177], v[156:157]
	v_pk_fma_f32 v[156:157], v[58:59], v[178:179], v[156:157]
	v_pk_add_f32 v[156:157], v[156:157], v[66:67]
	s_nop 0
	v_mul_f32_e32 v180, 0xbfb8aa3b, v156
	v_exp_f32_e32 v186, v180
	v_mul_f32_e32 v180, 0xbfb8aa3b, v157
	v_exp_f32_e32 v187, v180
	s_nop 0
	v_pk_add_f32 v[186:187], v[186:187], 1.0 op_sel_hi:[1,0]
	s_nop 0
	v_rcp_f32_e32 v186, v186
	v_rcp_f32_e32 v187, v187
	s_nop 0
	v_pk_mul_f32 v[156:157], v[156:157], v[186:187]
	s_nop 0
	v_cvt_pk_bf16_f32 v190, v150, v151
	v_cvt_pk_bf16_f32 v191, v152, v153
	v_cvt_pk_bf16_f32 v192, v154, v155
	v_cvt_pk_bf16_f32 v193, v156, v157
	global_store_dwordx4 v[6:7], v[190:193], off
	s_waitcnt vmcnt(1)
	v_cndmask_b32_e64 v122, 0, v122, s[42:43]
	v_cndmask_b32_e64 v130, 0, v130, s[44:45]
	v_lshlrev_b32_e32 v174, 16, v126
	v_and_b32_e32 v175, 0xffff0000, v126
	v_lshlrev_b32_e32 v176, 16, v122
	v_and_b32_e32 v177, 0xffff0000, v122
	v_lshlrev_b32_e32 v178, 16, v130
	v_and_b32_e32 v179, 0xffff0000, v130
	v_pk_mul_f32 v[150:151], v[76:77], v[174:175]
	s_nop 0
	v_pk_fma_f32 v[150:151], v[68:69], v[176:177], v[150:151]
	v_pk_fma_f32 v[150:151], v[86:87], v[178:179], v[150:151]
	v_pk_add_f32 v[150:151], v[150:151], v[94:95]
	s_nop 0
	v_mul_f32_e32 v180, 0xbfb8aa3b, v150
	v_exp_f32_e32 v186, v180
	v_mul_f32_e32 v180, 0xbfb8aa3b, v151
	v_exp_f32_e32 v187, v180
	s_nop 0
	v_pk_add_f32 v[186:187], v[186:187], 1.0 op_sel_hi:[1,0]
	s_nop 0
	v_rcp_f32_e32 v186, v186
	v_rcp_f32_e32 v187, v187
	s_nop 0
	v_pk_mul_f32 v[150:151], v[150:151], v[186:187]
	s_nop 0
	v_cndmask_b32_e64 v123, 0, v123, s[42:43]
	v_cndmask_b32_e64 v131, 0, v131, s[44:45]
	v_lshlrev_b32_e32 v174, 16, v127
	v_and_b32_e32 v175, 0xffff0000, v127
	v_lshlrev_b32_e32 v176, 16, v123
	v_and_b32_e32 v177, 0xffff0000, v123
	v_lshlrev_b32_e32 v178, 16, v131
	v_and_b32_e32 v179, 0xffff0000, v131
	v_pk_mul_f32 v[152:153], v[78:79], v[174:175]
	s_nop 0
	v_pk_fma_f32 v[152:153], v[70:71], v[176:177], v[152:153]
	v_pk_fma_f32 v[152:153], v[88:89], v[178:179], v[152:153]
	v_pk_add_f32 v[152:153], v[152:153], v[96:97]
	s_nop 0
	v_mul_f32_e32 v180, 0xbfb8aa3b, v152
	v_exp_f32_e32 v186, v180
	v_mul_f32_e32 v180, 0xbfb8aa3b, v153
	v_exp_f32_e32 v187, v180
	s_nop 0
	v_pk_add_f32 v[186:187], v[186:187], 1.0 op_sel_hi:[1,0]
	s_nop 0
	v_rcp_f32_e32 v186, v186
	v_rcp_f32_e32 v187, v187
	s_nop 0
	v_pk_mul_f32 v[152:153], v[152:153], v[186:187]
	s_nop 0
	v_cndmask_b32_e64 v124, 0, v124, s[42:43]
	v_cndmask_b32_e64 v132, 0, v132, s[44:45]
	v_lshlrev_b32_e32 v174, 16, v128
	v_and_b32_e32 v175, 0xffff0000, v128
	v_lshlrev_b32_e32 v176, 16, v124
	v_and_b32_e32 v177, 0xffff0000, v124
	v_lshlrev_b32_e32 v178, 16, v132
	v_and_b32_e32 v179, 0xffff0000, v132
	v_pk_mul_f32 v[154:155], v[80:81], v[174:175]
	s_nop 0
	v_pk_fma_f32 v[154:155], v[72:73], v[176:177], v[154:155]
	v_pk_fma_f32 v[154:155], v[90:91], v[178:179], v[154:155]
	v_pk_add_f32 v[154:155], v[154:155], v[98:99]
	s_nop 0
	v_mul_f32_e32 v180, 0xbfb8aa3b, v154
	v_exp_f32_e32 v186, v180
	v_mul_f32_e32 v180, 0xbfb8aa3b, v155
	v_exp_f32_e32 v187, v180
	s_nop 0
	v_pk_add_f32 v[186:187], v[186:187], 1.0 op_sel_hi:[1,0]
	s_nop 0
	v_rcp_f32_e32 v186, v186
	v_rcp_f32_e32 v187, v187
	s_nop 0
	v_pk_mul_f32 v[154:155], v[154:155], v[186:187]
	s_nop 0
	v_cndmask_b32_e64 v125, 0, v125, s[42:43]
	v_cndmask_b32_e64 v133, 0, v133, s[44:45]
	v_lshlrev_b32_e32 v174, 16, v129
	v_and_b32_e32 v175, 0xffff0000, v129
	v_lshlrev_b32_e32 v176, 16, v125
	v_and_b32_e32 v177, 0xffff0000, v125
	v_lshlrev_b32_e32 v178, 16, v133
	v_and_b32_e32 v179, 0xffff0000, v133
	v_pk_mul_f32 v[156:157], v[82:83], v[174:175]
	s_nop 0
	v_pk_fma_f32 v[156:157], v[74:75], v[176:177], v[156:157]
	v_pk_fma_f32 v[156:157], v[92:93], v[178:179], v[156:157]
	v_pk_add_f32 v[156:157], v[156:157], v[100:101]
	s_nop 0
	v_mul_f32_e32 v180, 0xbfb8aa3b, v156
	v_exp_f32_e32 v186, v180
	v_mul_f32_e32 v180, 0xbfb8aa3b, v157
	v_exp_f32_e32 v187, v180
	s_nop 0
	v_pk_add_f32 v[186:187], v[186:187], 1.0 op_sel_hi:[1,0]
	s_nop 0
	v_rcp_f32_e32 v186, v186
	v_rcp_f32_e32 v187, v187
	s_nop 0
	v_pk_mul_f32 v[156:157], v[156:157], v[186:187]
	s_nop 0
	v_cvt_pk_bf16_f32 v170, v150, v151
	v_cvt_pk_bf16_f32 v171, v152, v153
	v_cvt_pk_bf16_f32 v172, v154, v155
	v_cvt_pk_bf16_f32 v173, v156, v157
	global_store_dwordx4 v[6:7], v[170:173], off offset:1024
	s_mov_b64 s[68:69], 0x1800
	v_lshl_add_u64 v[0:1], v[0:1], 0, s[68:69]
	s_mov_b64 s[68:69], 0x800
	v_lshl_add_u64 v[6:7], v[6:7], 0, s[68:69]
	s_add_i32 s70, s70, 1
	s_cmp_lg_u32 s70, 4
	s_cbranch_scc1 .Lcv_odd_tok
	s_branch .LBB0_275
.Lcv_even:
	s_mov_b64 s[68:69], 0x1800
	v_lshl_add_u64 v[162:163], v[8:9], 0, s[68:69]
	s_mov_b64 s[68:69], 0x3000
	v_lshl_add_u64 v[164:165], v[8:9], 0, s[68:69]
	s_mov_b64 s[68:69], 0x1000
	v_lshl_add_u64 v[166:167], v[8:9], 0, s[68:69]
	v_lshl_add_u64 v[168:169], v[162:163], 0, s[68:69]
	v_lshl_add_u64 v[170:171], v[164:165], 0, s[68:69]
	global_load_dwordx4 v[36:39], v[8:9], off
	global_load_dwordx4 v[40:43], v[8:9], off offset:16
	global_load_dwordx4 v[44:47], v[162:163], off
	global_load_dwordx4 v[48:51], v[162:163], off offset:16
	global_load_dwordx4 v[52:55], v[164:165], off
	global_load_dwordx4 v[56:59], v[164:165], off offset:16
	global_load_dwordx4 v[60:63], v[8:9], off offset:2048
	global_load_dwordx4 v[64:67], v[8:9], off offset:2064
	global_load_dwordx4 v[68:71], v[162:163], off offset:2048
	global_load_dwordx4 v[72:75], v[162:163], off offset:2064
	global_load_dwordx4 v[76:79], v[164:165], off offset:2048
	global_load_dwordx4 v[80:83], v[164:165], off offset:2064
	global_load_dwordx4 v[86:89], v[166:167], off
	global_load_dwordx4 v[90:93], v[166:167], off offset:16
	global_load_dwordx4 v[94:97], v[168:169], off
	global_load_dwordx4 v[98:101], v[168:169], off offset:16
	global_load_dwordx4 v[102:105], v[170:171], off
	global_load_dwordx4 v[106:109], v[170:171], off offset:16
	s_waitcnt vmcnt(0)
.Lcv_even_tok:
	v_add_u32_e32 v12, s70, v23
	v_cmp_lt_i32_e32 vcc, s2, v12
	v_mov_b32_e32 v13, 0xff
	v_mov_b32_e32 v14, 0xfff
	v_cndmask_b32_e32 v13, v13, v14, vcc
	v_and_b32_e32 v12, v13, v12
	v_cmp_ne_u32_e64 s[42:43], 0, v12
	v_cmp_ne_u32_e64 s[44:45], v12, v13
	s_mov_b64 s[68:69], 0xa91f800
	v_lshl_add_u64 v[162:163], v[0:1], 0, s[68:69]
	s_mov_b64 s[68:69], 0xa921000
	v_lshl_add_u64 v[164:165], v[0:1], 0, s[68:69]
	s_mov_b64 s[68:69], 0xa922800
	v_lshl_add_u64 v[166:167], v[0:1], 0, s[68:69]
	global_load_dwordx4 v[110:113], v[162:163], off
	global_load_dwordx4 v[114:117], v[164:165], off
	global_load_dwordx4 v[118:121], v[166:167], off
	global_load_dwordx4 v[122:125], v[162:163], off offset:1024
	global_load_dwordx4 v[126:129], v[164:165], off offset:1024
	global_load_dwordx4 v[130:133], v[166:167], off offset:1024
	global_load_dwordx4 v[134:137], v[162:163], off offset:2048
	global_load_dwordx4 v[138:141], v[164:165], off offset:2048
	global_load_dwordx4 v[142:145], v[166:167], off offset:2048
	s_waitcnt vmcnt(6)
	v_cndmask_b32_e64 v110, 0, v110, s[42:43]
	v_cndmask_b32_e64 v118, 0, v118, s[44:45]
	v_lshlrev_b32_e32 v174, 16, v114
	v_and_b32_e32 v175, 0xffff0000, v114
	v_lshlrev_b32_e32 v176, 16, v110
	v_and_b32_e32 v177, 0xffff0000, v110
	v_lshlrev_b32_e32 v178, 16, v118
	v_and_b32_e32 v179, 0xffff0000, v118
	v_pk_mul_f32 v[150:151], v[44:45], v[174:175]
	s_nop 0
	v_pk_fma_f32 v[150:151], v[36:37], v[176:177], v[150:151]
	v_pk_fma_f32 v[150:151], v[52:53], v[178:179], v[150:151]
	s_nop 0
	v_mul_f32_e32 v180, 0xbfb8aa3b, v150
	v_exp_f32_e32 v186, v180
	v_mul_f32_e32 v180, 0xbfb8aa3b, v151
	v_exp_f32_e32 v187, v180
	s_nop 0
	v_pk_add_f32 v[186:187], v[186:187], 1.0 op_sel_hi:[1,0]
	s_nop 0
	v_rcp_f32_e32 v186, v186
	v_rcp_f32_e32 v187, v187
	s_nop 0
	v_pk_mul_f32 v[150:151], v[150:151], v[186:187]
	s_nop 0
	v_cndmask_b32_e64 v111, 0, v111, s[42:43]
	v_cndmask_b32_e64 v119, 0, v119, s[44:45]
	v_lshlrev_b32_e32 v174, 16, v115
	v_and_b32_e32 v175, 0xffff0000, v115
	v_lshlrev_b32_e32 v176, 16, v111
	v_and_b32_e32 v177, 0xffff0000, v111
	v_lshlrev_b32_e32 v178, 16, v119
	v_and_b32_e32 v179, 0xffff0000, v119
	v_pk_mul_f32 v[152:153], v[46:47], v[174:175]
	s_nop 0
	v_pk_fma_f32 v[152:153], v[38:39], v[176:177], v[152:153]
	v_pk_fma_f32 v[152:153], v[54:55], v[178:179], v[152:153]
	s_nop 0
	v_mul_f32_e32 v180, 0xbfb8aa3b, v152
	v_exp_f32_e32 v186, v180
	v_mul_f32_e32 v180, 0xbfb8aa3b, v153
	v_exp_f32_e32 v187, v180
	s_nop 0
	v_pk_add_f32 v[186:187], v[186:187], 1.0 op_sel_hi:[1,0]
	s_nop 0
	v_rcp_f32_e32 v186, v186
	v_rcp_f32_e32 v187, v187
	s_nop 0
	v_pk_mul_f32 v[152:153], v[152:153], v[186:187]
	s_nop 0
	v_cndmask_b32_e64 v112, 0, v112, s[42:43]
	v_cndmask_b32_e64 v120, 0, v120, s[44:45]
	v_lshlrev_b32_e32 v174, 16, v116
	v_and_b32_e32 v175, 0xffff0000, v116
	v_lshlrev_b32_e32 v176, 16, v112
	v_and_b32_e32 v177, 0xffff0000, v112
	v_lshlrev_b32_e32 v178, 16, v120
	v_and_b32_e32 v179, 0xffff0000, v120
	v_pk_mul_f32 v[154:155], v[48:49], v[174:175]
	s_nop 0
	v_pk_fma_f32 v[154:155], v[40:41], v[176:177], v[154:155]
	v_pk_fma_f32 v[154:155], v[56:57], v[178:179], v[154:155]
	s_nop 0
	v_mul_f32_e32 v180, 0xbfb8aa3b, v154
	v_exp_f32_e32 v186, v180
	v_mul_f32_e32 v180, 0xbfb8aa3b, v155
	v_exp_f32_e32 v187, v180
	s_nop 0
	v_pk_add_f32 v[186:187], v[186:187], 1.0 op_sel_hi:[1,0]
	s_nop 0
	v_rcp_f32_e32 v186, v186
	v_rcp_f32_e32 v187, v187
	s_nop 0
	v_pk_mul_f32 v[154:155], v[154:155], v[186:187]
	s_nop 0
	v_cndmask_b32_e64 v113, 0, v113, s[42:43]
	v_cndmask_b32_e64 v121, 0, v121, s[44:45]
	v_lshlrev_b32_e32 v174, 16, v117
	v_and_b32_e32 v175, 0xffff0000, v117
	v_lshlrev_b32_e32 v176, 16, v113
	v_and_b32_e32 v177, 0xffff0000, v113
	v_lshlrev_b32_e32 v178, 16, v121
	v_and_b32_e32 v179, 0xffff0000, v121
	v_pk_mul_f32 v[156:157], v[50:51], v[174:175]
	s_nop 0
	v_pk_fma_f32 v[156:157], v[42:43], v[176:177], v[156:157]
	v_pk_fma_f32 v[156:157], v[58:59], v[178:179], v[156:157]
	s_nop 0
	v_mul_f32_e32 v180, 0xbfb8aa3b, v156
	v_exp_f32_e32 v186, v180
	v_mul_f32_e32 v180, 0xbfb8aa3b, v157
	v_exp_f32_e32 v187, v180
	s_nop 0
	v_pk_add_f32 v[186:187], v[186:187], 1.0 op_sel_hi:[1,0]
	s_nop 0
	v_rcp_f32_e32 v186, v186
	v_rcp_f32_e32 v187, v187
	s_nop 0
	v_pk_mul_f32 v[156:157], v[156:157], v[186:187]
	s_nop 0
	v_mul_f32_e32 v188, v150, v150
	v_fmac_f32_e32 v188, v151, v151
	v_fmac_f32_e32 v188, v152, v152
	v_fmac_f32_e32 v188, v153, v153
	v_fmac_f32_e32 v188, v154, v154
	v_fmac_f32_e32 v188, v155, v155
	v_fmac_f32_e32 v188, v156, v156
	v_fmac_f32_e32 v188, v157, v157
	s_nop 1
	v_add_f32_dpp v188, v188, v188 quad_perm:[1,0,3,2] row_mask:0xf bank_mask:0xf
	s_nop 1
	v_add_f32_dpp v188, v188, v188 quad_perm:[2,3,0,1] row_mask:0xf bank_mask:0xf
	s_nop 1
	v_add_f32_dpp v188, v188, v188 row_half_mirror row_mask:0xf bank_mask:0xf
	s_nop 1
	v_add_f32_dpp v188, v188, v188 row_mirror row_mask:0xf bank_mask:0xf
	s_nop 0
	v_add_f32_e32 v188, 0x358637bd, v188
	v_cmp_gt_f32_e32 vcc, s3, v188
	v_mul_f32_e32 v189, 0x4b800000, v188
	s_nop 0
	v_cndmask_b32_e32 v188, v188, v189, vcc
	v_rsq_f32_e32 v188, v188
	s_nop 0
	v_mul_f32_e32 v189, 0x45800000, v188
	v_cndmask_b32_e32 v188, v188, v189, vcc
	v_mul_f32_e32 v188, 0x3db504f3, v188
	s_nop 0
	v_pk_mul_f32 v[150:151], v[150:151], v[188:189] op_sel_hi:[1,0]
	v_pk_mul_f32 v[152:153], v[152:153], v[188:189] op_sel_hi:[1,0]
	v_pk_mul_f32 v[154:155], v[154:155], v[188:189] op_sel_hi:[1,0]
	v_pk_mul_f32 v[156:157], v[156:157], v[188:189] op_sel_hi:[1,0]
	s_nop 0
	v_cvt_pk_bf16_f32 v190, v150, v151
	v_cvt_pk_bf16_f32 v191, v152, v153
	v_cvt_pk_bf16_f32 v192, v154, v155
	v_cvt_pk_bf16_f32 v193, v156, v157
	global_store_dwordx4 v[10:11], v[190:193], off
	s_waitcnt vmcnt(4)
	v_cndmask_b32_e64 v122, 0, v122, s[42:43]
	v_cndmask_b32_e64 v130, 0, v130, s[44:45]
	v_lshlrev_b32_e32 v174, 16, v126
	v_and_b32_e32 v175, 0xffff0000, v126
	v_lshlrev_b32_e32 v176, 16, v122
	v_and_b32_e32 v177, 0xffff0000, v122
	v_lshlrev_b32_e32 v178, 16, v130
	v_and_b32_e32 v179, 0xffff0000, v130
	v_pk_mul_f32 v[150:151], v[68:69], v[174:175]
	s_nop 0
	v_pk_fma_f32 v[150:151], v[60:61], v[176:177], v[150:151]
	v_pk_fma_f32 v[150:151], v[76:77], v[178:179], v[150:151]
	s_nop 0
	v_mul_f32_e32 v180, 0xbfb8aa3b, v150
	v_exp_f32_e32 v186, v180
	v_mul_f32_e32 v180, 0xbfb8aa3b, v151
	v_exp_f32_e32 v187, v180
	s_nop 0
	v_pk_add_f32 v[186:187], v[186:187], 1.0 op_sel_hi:[1,0]
	s_nop 0
	v_rcp_f32_e32 v186, v186
	v_rcp_f32_e32 v187, v187
	s_nop 0
	v_pk_mul_f32 v[150:151], v[150:151], v[186:187]
	s_nop 0
	v_cndmask_b32_e64 v123, 0, v123, s[42:43]
	v_cndmask_b32_e64 v131, 0, v131, s[44:45]
	v_lshlrev_b32_e32 v174, 16, v127
	v_and_b32_e32 v175, 0xffff0000, v127
	v_lshlrev_b32_e32 v176, 16, v123
	v_and_b32_e32 v177, 0xffff0000, v123
	v_lshlrev_b32_e32 v178, 16, v131
	v_and_b32_e32 v179, 0xffff0000, v131
	v_pk_mul_f32 v[152:153], v[70:71], v[174:175]
	s_nop 0
	v_pk_fma_f32 v[152:153], v[62:63], v[176:177], v[152:153]
	v_pk_fma_f32 v[152:153], v[78:79], v[178:179], v[152:153]
	s_nop 0
	v_mul_f32_e32 v180, 0xbfb8aa3b, v152
	v_exp_f32_e32 v186, v180
	v_mul_f32_e32 v180, 0xbfb8aa3b, v153
	v_exp_f32_e32 v187, v180
	s_nop 0
	v_pk_add_f32 v[186:187], v[186:187], 1.0 op_sel_hi:[1,0]
	s_nop 0
	v_rcp_f32_e32 v186, v186
	v_rcp_f32_e32 v187, v187
	s_nop 0
	v_pk_mul_f32 v[152:153], v[152:153], v[186:187]
	s_nop 0
	v_cndmask_b32_e64 v124, 0, v124, s[42:43]
	v_cndmask_b32_e64 v132, 0, v132, s[44:45]
	v_lshlrev_b32_e32 v174, 16, v128
	v_and_b32_e32 v175, 0xffff0000, v128
	v_lshlrev_b32_e32 v176, 16, v124
	v_and_b32_e32 v177, 0xffff0000, v124
	v_lshlrev_b32_e32 v178, 16, v132
	v_and_b32_e32 v179, 0xffff0000, v132
	v_pk_mul_f32 v[154:155], v[72:73], v[174:175]
	s_nop 0
	v_pk_fma_f32 v[154:155], v[64:65], v[176:177], v[154:155]
	v_pk_fma_f32 v[154:155], v[80:81], v[178:179], v[154:155]
	s_nop 0
	v_mul_f32_e32 v180, 0xbfb8aa3b, v154
	v_exp_f32_e32 v186, v180
	v_mul_f32_e32 v180, 0xbfb8aa3b, v155
	v_exp_f32_e32 v187, v180
	s_nop 0
	v_pk_add_f32 v[186:187], v[186:187], 1.0 op_sel_hi:[1,0]
	s_nop 0
	v_rcp_f32_e32 v186, v186
	v_rcp_f32_e32 v187, v187
	s_nop 0
	v_pk_mul_f32 v[154:155], v[154:155], v[186:187]
	s_nop 0
	v_cndmask_b32_e64 v125, 0, v125, s[42:43]
	v_cndmask_b32_e64 v133, 0, v133, s[44:45]
	v_lshlrev_b32_e32 v174, 16, v129
	v_and_b32_e32 v175, 0xffff0000, v129
	v_lshlrev_b32_e32 v176, 16, v125
	v_and_b32_e32 v177, 0xffff0000, v125
	v_lshlrev_b32_e32 v178, 16, v133
	v_and_b32_e32 v179, 0xffff0000, v133
	v_pk_mul_f32 v[156:157], v[74:75], v[174:175]
	s_nop 0
	v_pk_fma_f32 v[156:157], v[66:67], v[176:177], v[156:157]
	v_pk_fma_f32 v[156:157], v[82:83], v[178:179], v[156:157]
	s_nop 0
	v_mul_f32_e32 v180, 0xbfb8aa3b, v156
	v_exp_f32_e32 v186, v180
	v_mul_f32_e32 v180, 0xbfb8aa3b, v157
	v_exp_f32_e32 v187, v180
	s_nop 0
	v_pk_add_f32 v[186:187], v[186:187], 1.0 op_sel_hi:[1,0]
	s_nop 0
	v_rcp_f32_e32 v186, v186
	v_rcp_f32_e32 v187, v187
	s_nop 0
	v_pk_mul_f32 v[156:157], v[156:157], v[186:187]
	s_nop 0
	v_mul_f32_e32 v188, v150, v150
	v_fmac_f32_e32 v188, v151, v151
	v_fmac_f32_e32 v188, v152, v152
	v_fmac_f32_e32 v188, v153, v153
	v_fmac_f32_e32 v188, v154, v154
	v_fmac_f32_e32 v188, v155, v155
	v_fmac_f32_e32 v188, v156, v156
	v_fmac_f32_e32 v188, v157, v157
	s_nop 1
	v_add_f32_dpp v188, v188, v188 quad_perm:[1,0,3,2] row_mask:0xf bank_mask:0xf
	s_nop 1
	v_add_f32_dpp v188, v188, v188 quad_perm:[2,3,0,1] row_mask:0xf bank_mask:0xf
	s_nop 1
	v_add_f32_dpp v188, v188, v188 row_half_mirror row_mask:0xf bank_mask:0xf
	s_nop 1
	v_add_f32_dpp v188, v188, v188 row_mirror row_mask:0xf bank_mask:0xf
	s_nop 0
	v_add_f32_e32 v188, 0x358637bd, v188
	v_cmp_gt_f32_e32 vcc, s3, v188
	v_mul_f32_e32 v189, 0x4b800000, v188
	s_nop 0
	v_cndmask_b32_e32 v188, v188, v189, vcc
	v_rsq_f32_e32 v188, v188
	s_nop 0
	v_mul_f32_e32 v189, 0x45800000, v188
	v_cndmask_b32_e32 v188, v188, v189, vcc
	s_nop 0
	v_pk_mul_f32 v[150:151], v[150:151], v[188:189] op_sel_hi:[1,0]
	v_pk_mul_f32 v[152:153], v[152:153], v[188:189] op_sel_hi:[1,0]
	v_pk_mul_f32 v[154:155], v[154:155], v[188:189] op_sel_hi:[1,0]
	v_pk_mul_f32 v[156:157], v[156:157], v[188:189] op_sel_hi:[1,0]
	s_nop 0
	v_cvt_pk_bf16_f32 v170, v150, v151
	v_cvt_pk_bf16_f32 v171, v152, v153
	v_cvt_pk_bf16_f32 v172, v154, v155
	v_cvt_pk_bf16_f32 v173, v156, v157
	global_store_dwordx4 v[10:11], v[170:173], off offset:1024
	s_waitcnt vmcnt(2)
	v_cndmask_b32_e64 v134, 0, v134, s[42:43]
	v_cndmask_b32_e64 v142, 0, v142, s[44:45]
	v_lshlrev_b32_e32 v174, 16, v138
	v_and_b32_e32 v175, 0xffff0000, v138
	v_lshlrev_b32_e32 v176, 16, v134
	v_and_b32_e32 v177, 0xffff0000, v134
	v_lshlrev_b32_e32 v178, 16, v142
	v_and_b32_e32 v179, 0xffff0000, v142
	v_pk_mul_f32 v[150:151], v[94:95], v[174:175]
	s_nop 0
	v_pk_fma_f32 v[150:151], v[86:87], v[176:177], v[150:151]
	v_pk_fma_f32 v[150:151], v[102:103], v[178:179], v[150:151]
	s_nop 0
	v_mul_f32_e32 v180, 0xbfb8aa3b, v150
	v_exp_f32_e32 v186, v180
	v_mul_f32_e32 v180, 0xbfb8aa3b, v151
	v_exp_f32_e32 v187, v180
	s_nop 0
	v_pk_add_f32 v[186:187], v[186:187], 1.0 op_sel_hi:[1,0]
	s_nop 0
	v_rcp_f32_e32 v186, v186
	v_rcp_f32_e32 v187, v187
	s_nop 0
	v_pk_mul_f32 v[150:151], v[150:151], v[186:187]
	s_nop 0
	v_cndmask_b32_e64 v135, 0, v135, s[42:43]
	v_cndmask_b32_e64 v143, 0, v143, s[44:45]
	v_lshlrev_b32_e32 v174, 16, v139
	v_and_b32_e32 v175, 0xffff0000, v139
	v_lshlrev_b32_e32 v176, 16, v135
	v_and_b32_e32 v177, 0xffff0000, v135
	v_lshlrev_b32_e32 v178, 16, v143
	v_and_b32_e32 v179, 0xffff0000, v143
	v_pk_mul_f32 v[152:153], v[96:97], v[174:175]
	s_nop 0
	v_pk_fma_f32 v[152:153], v[88:89], v[176:177], v[152:153]
	v_pk_fma_f32 v[152:153], v[104:105], v[178:179], v[152:153]
	s_nop 0
	v_mul_f32_e32 v180, 0xbfb8aa3b, v152
	v_exp_f32_e32 v186, v180
	v_mul_f32_e32 v180, 0xbfb8aa3b, v153
	v_exp_f32_e32 v187, v180
	s_nop 0
	v_pk_add_f32 v[186:187], v[186:187], 1.0 op_sel_hi:[1,0]
	s_nop 0
	v_rcp_f32_e32 v186, v186
	v_rcp_f32_e32 v187, v187
	s_nop 0
	v_pk_mul_f32 v[152:153], v[152:153], v[186:187]
	s_nop 0
	v_cndmask_b32_e64 v136, 0, v136, s[42:43]
	v_cndmask_b32_e64 v144, 0, v144, s[44:45]
	v_lshlrev_b32_e32 v174, 16, v140
	v_and_b32_e32 v175, 0xffff0000, v140
	v_lshlrev_b32_e32 v176, 16, v136
	v_and_b32_e32 v177, 0xffff0000, v136
	v_lshlrev_b32_e32 v178, 16, v144
	v_and_b32_e32 v179, 0xffff0000, v144
	v_pk_mul_f32 v[154:155], v[98:99], v[174:175]
	s_nop 0
	v_pk_fma_f32 v[154:155], v[90:91], v[176:177], v[154:155]
	v_pk_fma_f32 v[154:155], v[106:107], v[178:179], v[154:155]
	s_nop 0
	v_mul_f32_e32 v180, 0xbfb8aa3b, v154
	v_exp_f32_e32 v186, v180
	v_mul_f32_e32 v180, 0xbfb8aa3b, v155
	v_exp_f32_e32 v187, v180
	s_nop 0
	v_pk_add_f32 v[186:187], v[186:187], 1.0 op_sel_hi:[1,0]
	s_nop 0
	v_rcp_f32_e32 v186, v186
	v_rcp_f32_e32 v187, v187
	s_nop 0
	v_pk_mul_f32 v[154:155], v[154:155], v[186:187]
	s_nop 0
	v_cndmask_b32_e64 v137, 0, v137, s[42:43]
	v_cndmask_b32_e64 v145, 0, v145, s[44:45]
	v_lshlrev_b32_e32 v174, 16, v141
	v_and_b32_e32 v175, 0xffff0000, v141
	v_lshlrev_b32_e32 v176, 16, v137
	v_and_b32_e32 v177, 0xffff0000, v137
	v_lshlrev_b32_e32 v178, 16, v145
	v_and_b32_e32 v179, 0xffff0000, v145
	v_pk_mul_f32 v[156:157], v[100:101], v[174:175]
	s_nop 0
	v_pk_fma_f32 v[156:157], v[92:93], v[176:177], v[156:157]
	v_pk_fma_f32 v[156:157], v[108:109], v[178:179], v[156:157]
	s_nop 0
	v_mul_f32_e32 v180, 0xbfb8aa3b, v156
	v_exp_f32_e32 v186, v180
	v_mul_f32_e32 v180, 0xbfb8aa3b, v157
	v_exp_f32_e32 v187, v180
	s_nop 0
	v_pk_add_f32 v[186:187], v[186:187], 1.0 op_sel_hi:[1,0]
	s_nop 0
	v_rcp_f32_e32 v186, v186
	v_rcp_f32_e32 v187, v187
	s_nop 0
	v_pk_mul_f32 v[156:157], v[156:157], v[186:187]
	s_nop 0
	v_cvt_pk_bf16_f32 v190, v150, v151
	v_cvt_pk_bf16_f32 v191, v152, v153
	v_cvt_pk_bf16_f32 v192, v154, v155
	v_cvt_pk_bf16_f32 v193, v156, v157
	global_store_dwordx4 v[10:11], v[190:193], off offset:2048
	s_mov_b64 s[68:69], 0x1800
	v_lshl_add_u64 v[0:1], v[0:1], 0, s[68:69]
	s_mov_b64 s[68:69], 0xc00
	v_lshl_add_u64 v[10:11], v[10:11], 0, s[68:69]
	s_add_i32 s70, s70, 1
	s_cmp_lg_u32 s70, 4
	s_cbranch_scc1 .Lcv_even_tok
